# phase3 q/kv up-projections: items sharing a 256-token row tile placed on one XCD (L2 serves the re-reads); all K-tiles of an item loaded up front into spare VGPRs
# speedup vs baseline: 1.1039x; 1.0094x over previous
.LBB0_395:
	s_or_b64 exec, exec, s[0:1]
	s_waitcnt lgkmcnt(0)
	v_mov_b32_e32 v0, v174
	s_cmpk_gt_i32 s90, 0x2ff
	s_barrier
	s_cbranch_scc1 .LBB0_486
	v_and_b32_e32 v113, 0xcf, v0
	v_ashrrev_i32_e32 v1, 2, v0
	v_lshrrev_b32_e32 v0, 2, v0
	v_and_b32_e32 v112, 12, v0
	v_mbcnt_hi_u32_b32 v128, -1, v164
	v_mov_b32_e32 v115, 0
	s_add_i32 s2, 0, 0x1b000
	v_or_b32_e32 v122, 16, v113
	v_or_b32_e32 v124, 32, v113
	v_or_b32_e32 v126, 48, v113
	v_lshlrev_b32_e32 v114, 2, v112
	v_and_b32_e32 v0, 64, v128
	v_and_b32_e32 v120, 0xffffffc0, v1
	v_lshl_add_u32 v121, v113, 2, s2
	v_lshl_add_u32 v123, v122, 2, s2
	v_lshl_add_u32 v125, v124, 2, s2
	v_lshl_add_u32 v127, v126, 2, s2
	v_lshl_add_u64 v[116:117], s[22:23], 0, v[114:115]
	s_lshl_b32 s3, s90, 7
	s_lshl_b32 s10, s88, 7
	s_mov_b32 s11, 0x2aaaaaab
	s_movk_i32 s33, 0x1040
	s_movk_i32 s35, 0xc0
	s_movk_i32 s38, 0x90
	s_add_i32 s39, 0, 0x12000
	v_xor_b32_e32 v129, 1, v128
	v_add_u32_e32 v130, 64, v0
	v_xor_b32_e32 v131, 2, v128
	v_xor_b32_e32 v132, 4, v128
	v_mov_b32_e32 v133, 0x358637bd
	s_mov_b32 s68, 0x800000
	s_mov_b64 s[12:13], 0xa0
	s_movk_i32 s69, 0x60
	v_mov_b32_e32 v134, 0xfcf
	v_mov_b32_e32 v135, 0xfdf
	v_mov_b32_e32 v136, 0xfef
	v_mov_b32_e32 v137, 0xfff
	s_mov_b32 s70, s90
	s_mov_b32 s98, s88
	s_movk_i32 s99, 0x300
	s_cmp_lg_u32 s88, 0x100
	s_cbranch_scc1 .Lp3q_noremap
	s_and_b32 s70, s90, 7
	s_mul_i32 s70, s70, 96
	s_lshr_b32 s98, s90, 3
	s_add_i32 s70, s70, s98
	s_lshl_b32 s3, s70, 7
	s_add_i32 s99, s70, 96
	s_movk_i32 s98, 32
	s_movk_i32 s10, 0x1000
.Lp3q_noremap:
	s_branch .LBB0_398
.LBB0_397:
	s_or_b64 exec, exec, s[0:1]
	s_waitcnt lgkmcnt(0)
	s_barrier
	s_add_i32 s70, s70, s98
	s_add_i32 s3, s3, s10
	s_cmp_lt_i32 s70, s99
	s_cbranch_scc0 .LBB0_486
.LBB0_398:
	s_mul_hi_i32 s6, s70, 0x2aaaaaab
	s_lshr_b32 s0, s6, 31
	s_add_i32 s6, s6, s0
	s_mul_i32 s7, s6, 0xfffffd00
	s_add_i32 s0, s3, s7
	s_ashr_i32 s1, s0, 31
	s_lshl_b32 s34, s6, 8
	s_lshl_b64 s[0:1], s[0:1], 9
	v_readlane_b32 s40, v241, 8
	v_readlane_b32 s72, v240, 1
	v_readlane_b32 s41, v241, 9
	v_readlane_b32 s42, v241, 10
	v_readlane_b32 s43, v241, 11
	v_readlane_b32 s44, v241, 12
	v_readlane_b32 s45, v241, 13
	v_readlane_b32 s46, v241, 14
	v_readlane_b32 s47, v241, 15
	s_add_u32 s0, s40, s0
	v_readlane_b32 s76, v240, 5
	v_readlane_b32 s77, v240, 6
	v_mov_b32_e32 v12, v174
	s_addc_u32 s1, s41, s1
	s_mul_i32 s4, s6, 0x104000
	v_readlane_b32 s78, v240, 7
	v_readlane_b32 s79, v240, 8
	v_readlane_b32 s80, v240, 9
	v_readlane_b32 s81, v240, 10
	v_readlane_b32 s82, v240, 11
	v_readlane_b32 s83, v240, 12
	v_readlane_b32 s84, v240, 13
	v_readlane_b32 s85, v240, 14
	v_readlane_b32 s86, v240, 15
	v_readlane_b32 s87, v240, 16
	s_mov_b64 s[40:41], s[76:77]
	s_mul_hi_i32 s5, s34, 0x1040
	v_ashrrev_i32_e32 v118, 3, v12
	s_add_u32 s4, s40, s4
	v_and_b32_e32 v138, 7, v12
	v_add_u32_e32 v6, 64, v118
	s_addc_u32 s5, s41, s5
	v_lshlrev_b32_e32 v114, 4, v138
	v_ashrrev_i32_e32 v119, 31, v118
	v_ashrrev_i32_e32 v7, 31, v6
	v_lshl_add_u64 v[2:3], s[0:1], 0, v[114:115]
	v_lshlrev_b64 v[0:1], 9, v[118:119]
	v_lshlrev_b64 v[4:5], 9, v[6:7]
	v_lshl_add_u64 v[10:11], s[4:5], 0, v[114:115]
	v_lshl_add_u64 v[0:1], v[2:3], 0, v[0:1]
	v_lshl_add_u64 v[2:3], v[2:3], 0, v[4:5]
	v_mad_i64_i32 v[4:5], s[0:1], v118, s33, v[10:11]
	global_load_dwordx4 v[16:19], v[0:1], off
	global_load_dwordx4 v[20:23], v[2:3], off
	global_load_dwordx4 v[24:27], v[4:5], off
	v_mad_i64_i32 v[6:7], s[0:1], v6, s33, v[10:11]
	v_add_u32_e32 v8, 0x80, v118
	global_load_dwordx4 v[72:75], v[6:7], off
	v_mad_i64_i32 v[8:9], s[0:1], v8, s33, v[10:11]
	v_add_u32_e32 v14, 0xc0, v118
	global_load_dwordx4 v[64:67], v[8:9], off
	v_mad_i64_i32 v[10:11], s[0:1], v14, s33, v[10:11]
	global_load_dwordx4 v[60:63], v[10:11], off
	global_load_dwordx4 v[200:203], v[0:1], off offset:128
	global_load_dwordx4 v[204:207], v[2:3], off offset:128
	global_load_dwordx4 v[208:211], v[4:5], off offset:128
	global_load_dwordx4 v[212:215], v[6:7], off offset:128
	global_load_dwordx4 v[216:219], v[8:9], off offset:128
	global_load_dwordx4 v[220:223], v[10:11], off offset:128
	global_load_dwordx4 v[224:227], v[0:1], off offset:256
	global_load_dwordx4 v[228:231], v[2:3], off offset:256
	global_load_dwordx4 v[232:235], v[4:5], off offset:256
	global_load_dwordx4 v[236:239], v[6:7], off offset:256
	global_load_dwordx4 v[244:247], v[8:9], off offset:256
	global_load_dwordx4 v[248:251], v[10:11], off offset:256
	v_mul_lo_u32 v14, v118, s38
	v_add3_u32 v14, 0, v114, v14
	v_and_b32_e32 v13, 15, v12
	s_mov_b32 s0, 0xfffffc0
	v_and_b32_e32 v139, 48, v12
	v_and_b32_e32 v45, 0xcf, v12
	v_add_u32_e32 v44, 0, v139
	v_mul_u32_u24_e32 v175, 0x90, v45
	v_add_u32_e32 v15, 0x2400, v14
	v_add_u32_e32 v119, 0x4800, v14
	v_readlane_b32 s73, v240, 2
	v_readlane_b32 s74, v240, 3
	v_readlane_b32 s75, v240, 4
	s_mov_b64 s[42:43], s[78:79]
	s_mov_b64 s[44:45], s[80:81]
	s_mov_b64 s[46:47], s[82:83]
	s_mov_b64 s[48:49], s[84:85]
	s_mov_b64 s[50:51], s[86:87]
	s_waitcnt vmcnt(17)
	ds_write_b128 v14, v[16:19]
	s_waitcnt vmcnt(16)
	ds_write_b128 v14, v[20:23] offset:9216
	s_waitcnt vmcnt(15)
	v_and_b32_e32 v17, 0xffff0000, v24
	v_lshlrev_b32_e32 v16, 16, v24
	v_mul_f32_e32 v114, v17, v17
	v_fmac_f32_e32 v114, v16, v16
	v_lshlrev_b32_e32 v16, 16, v25
	v_fmac_f32_e32 v114, v16, v16
	v_and_b32_e32 v16, 0xffff0000, v25
	v_fmac_f32_e32 v114, v16, v16
	v_lshlrev_b32_e32 v16, 16, v26
	v_fmac_f32_e32 v114, v16, v16
	v_and_b32_e32 v16, 0xffff0000, v26
	v_fmac_f32_e32 v114, v16, v16
	v_lshlrev_b32_e32 v16, 16, v27
	ds_write_b128 v14, v[24:27] offset:18432
	s_waitcnt vmcnt(14)
	ds_write_b128 v14, v[72:75] offset:27648
	s_waitcnt vmcnt(13)
	ds_write_b128 v14, v[64:67] offset:36864
	s_waitcnt vmcnt(12)
	ds_write_b128 v14, v[60:63] offset:46080
	v_fmac_f32_e32 v114, v16, v16
	v_and_b32_e32 v16, 0xffff0000, v27
	v_fmac_f32_e32 v114, v16, v16
	s_waitcnt lgkmcnt(0)
	s_barrier
	v_lshrrev_b32_e32 v16, 2, v12
	v_and_or_b32 v13, v16, s0, v13
	v_mad_u64_u32 v[12:13], s[0:1], v13, s38, v[44:45]
	v_mad_u32_u24 v13, v45, s38, v44
	ds_read_b128 v[28:31], v12
	ds_read_b128 v[32:35], v12 offset:2304
	ds_read_b128 v[36:39], v12 offset:4608
	ds_read_b128 v[40:43], v12 offset:6912
	ds_read_b128 v[44:47], v13 offset:18432
	ds_read_b128 v[48:51], v13 offset:20736
	ds_read_b128 v[52:55], v13 offset:23040
	ds_read_b128 v[56:59], v13 offset:25344
	s_setprio 1
	s_waitcnt lgkmcnt(3)
	v_mfma_f32_16x16x32_bf16 v[80:83], v[28:31], v[44:47], 0
	s_waitcnt lgkmcnt(2)
	v_mfma_f32_16x16x32_bf16 v[84:87], v[28:31], v[48:51], 0
	s_waitcnt lgkmcnt(1)
	v_mfma_f32_16x16x32_bf16 v[92:95], v[28:31], v[52:55], 0
	s_waitcnt lgkmcnt(0)
	v_mfma_f32_16x16x32_bf16 v[28:31], v[28:31], v[56:59], 0
	v_mfma_f32_16x16x32_bf16 v[96:99], v[32:35], v[44:47], 0
	v_mfma_f32_16x16x32_bf16 v[100:103], v[32:35], v[48:51], 0
	v_mfma_f32_16x16x32_bf16 v[104:107], v[32:35], v[52:55], 0
	v_mfma_f32_16x16x32_bf16 v[32:35], v[32:35], v[56:59], 0
	v_mfma_f32_16x16x32_bf16 v[108:111], v[36:39], v[44:47], 0
	v_mfma_f32_16x16x32_bf16 v[140:143], v[36:39], v[48:51], 0
	v_mfma_f32_16x16x32_bf16 v[144:147], v[36:39], v[52:55], 0
	v_mfma_f32_16x16x32_bf16 v[36:39], v[36:39], v[56:59], 0
	v_mfma_f32_16x16x32_bf16 v[44:47], v[40:43], v[44:47], 0
	v_mfma_f32_16x16x32_bf16 v[48:51], v[40:43], v[48:51], 0
	v_mfma_f32_16x16x32_bf16 v[52:55], v[40:43], v[52:55], 0
	v_mfma_f32_16x16x32_bf16 v[40:43], v[40:43], v[56:59], 0
	s_setprio 0
	ds_read_b128 v[56:59], v12 offset:64
	ds_read_b128 v[148:151], v12 offset:2368
	ds_read_b128 v[152:155], v12 offset:4672
	ds_read_b128 v[156:159], v12 offset:6976
	ds_read_b128 v[160:163], v13 offset:18496
	ds_read_b128 v[166:169], v13 offset:20800
	ds_read_b128 v[170:173], v13 offset:23104
	ds_read_b128 v[176:179], v13 offset:25408
	s_setprio 1
	s_waitcnt lgkmcnt(3)
	v_mfma_f32_16x16x32_bf16 v[180:183], v[56:59], v[160:163], v[80:83]
	s_waitcnt lgkmcnt(2)
	v_mfma_f32_16x16x32_bf16 v[84:87], v[56:59], v[166:169], v[84:87]
	s_waitcnt lgkmcnt(1)
	v_mfma_f32_16x16x32_bf16 v[92:95], v[56:59], v[170:173], v[92:95]
	s_waitcnt lgkmcnt(0)
	v_mfma_f32_16x16x32_bf16 v[28:31], v[56:59], v[176:179], v[28:31]
	v_mfma_f32_16x16x32_bf16 v[56:59], v[148:151], v[160:163], v[96:99]
	v_mfma_f32_16x16x32_bf16 v[100:103], v[148:151], v[166:169], v[100:103]
	v_mfma_f32_16x16x32_bf16 v[32:35], v[148:151], v[176:179], v[32:35]
	v_mfma_f32_16x16x32_bf16 v[108:111], v[152:155], v[160:163], v[108:111]
	v_mfma_f32_16x16x32_bf16 v[140:143], v[152:155], v[166:169], v[140:143]
	v_mfma_f32_16x16x32_bf16 v[36:39], v[152:155], v[176:179], v[36:39]
	v_mfma_f32_16x16x32_bf16 v[44:47], v[156:159], v[160:163], v[44:47]
	v_mfma_f32_16x16x32_bf16 v[48:51], v[156:159], v[166:169], v[48:51]
	v_mfma_f32_16x16x32_bf16 v[52:55], v[156:159], v[170:173], v[52:55]
	v_mfma_f32_16x16x32_bf16 v[40:43], v[156:159], v[176:179], v[40:43]
	v_mfma_f32_16x16x32_bf16 v[184:187], v[148:151], v[170:173], v[104:107]
	v_mfma_f32_16x16x32_bf16 v[144:147], v[152:155], v[170:173], v[144:147]
	s_setprio 0
	v_add_u32_e32 v196, 0xd800, v14
	s_waitcnt vmcnt(11)
	v_mov_b32_e32 v16, v200
	v_mov_b32_e32 v17, v201
	v_mov_b32_e32 v18, v202
	v_mov_b32_e32 v19, v203
	ds_write_b128 v14, v[16:19] offset:55296
	s_waitcnt vmcnt(10)
	v_mov_b32_e32 v20, v204
	v_mov_b32_e32 v21, v205
	v_mov_b32_e32 v22, v206
	v_mov_b32_e32 v23, v207
	ds_write_b128 v14, v[20:23] offset:64512
	s_waitcnt vmcnt(9)
	v_mov_b32_e32 v24, v208
	v_mov_b32_e32 v25, v209
	v_mov_b32_e32 v26, v210
	v_mov_b32_e32 v27, v211
	ds_write_b128 v15, v[24:27] offset:64512
	s_waitcnt vmcnt(8)
	v_mov_b32_e32 v88, v212
	v_mov_b32_e32 v89, v213
	v_mov_b32_e32 v90, v214
	v_mov_b32_e32 v91, v215
	ds_write_b128 v119, v[88:91] offset:64512
	s_waitcnt vmcnt(7)
	v_mov_b32_e32 v76, v216
	v_mov_b32_e32 v77, v217
	v_mov_b32_e32 v78, v218
	v_mov_b32_e32 v79, v219
	ds_write_b128 v196, v[76:79] offset:36864
	s_waitcnt vmcnt(6)
	v_mov_b32_e32 v68, v220
	v_mov_b32_e32 v69, v221
	v_mov_b32_e32 v70, v222
	v_mov_b32_e32 v71, v223
	ds_write_b128 v196, v[68:71] offset:46080
	s_waitcnt lgkmcnt(0)
	s_barrier
	global_load_dwordx4 v[200:203], v[0:1], off offset:384
	global_load_dwordx4 v[204:207], v[2:3], off offset:384
	global_load_dwordx4 v[208:211], v[4:5], off offset:384
	global_load_dwordx4 v[212:215], v[6:7], off offset:384
	global_load_dwordx4 v[216:219], v[8:9], off offset:384
	global_load_dwordx4 v[220:223], v[10:11], off offset:384
	v_and_b32_e32 v192, 0xffff0000, v27
	v_lshlrev_b32_e32 v193, 16, v27
	v_and_b32_e32 v27, 0xffff0000, v24
	v_lshlrev_b32_e32 v24, 16, v24
	v_fmac_f32_e32 v114, v24, v24
	v_and_b32_e32 v194, 0xffff0000, v26
	v_lshlrev_b32_e32 v195, 16, v26
	v_and_b32_e32 v26, 0xffff0000, v25
	v_lshlrev_b32_e32 v25, 16, v25
	v_fmac_f32_e32 v114, v27, v27
	v_fmac_f32_e32 v114, v25, v25
	v_add3_u32 v139, s39, v139, v175
	v_fmac_f32_e32 v114, v26, v26
	ds_read_b128 v[24:27], v12 offset:55296
	ds_read_b128 v[152:155], v12 offset:57600
	ds_read_b128 v[156:159], v12 offset:59904
	ds_read_b128 v[160:163], v12 offset:62208
	ds_read_b128 v[166:169], v139
	ds_read_b128 v[170:173], v139 offset:2304
	ds_read_b128 v[176:179], v139 offset:4608
	ds_read_b128 v[188:191], v139 offset:6912
	v_fmac_f32_e32 v114, v195, v195
	v_fmac_f32_e32 v114, v194, v194
	v_fmac_f32_e32 v114, v193, v193
	v_fmac_f32_e32 v114, v192, v192
	s_setprio 1
	s_waitcnt lgkmcnt(3)
	v_mfma_f32_16x16x32_bf16 v[180:183], v[24:27], v[166:169], v[180:183]
	s_waitcnt lgkmcnt(2)
	v_mfma_f32_16x16x32_bf16 v[84:87], v[24:27], v[170:173], v[84:87]
	s_waitcnt lgkmcnt(1)
	v_mfma_f32_16x16x32_bf16 v[92:95], v[24:27], v[176:179], v[92:95]
	s_waitcnt lgkmcnt(0)
	v_mfma_f32_16x16x32_bf16 v[24:27], v[24:27], v[188:191], v[28:31]
	v_mfma_f32_16x16x32_bf16 v[28:31], v[152:155], v[166:169], v[56:59]
	v_mfma_f32_16x16x32_bf16 v[56:59], v[152:155], v[170:173], v[100:103]
	v_mfma_f32_16x16x32_bf16 v[100:103], v[152:155], v[176:179], v[184:187]
	v_mfma_f32_16x16x32_bf16 v[32:35], v[152:155], v[188:191], v[32:35]
	v_mfma_f32_16x16x32_bf16 v[108:111], v[156:159], v[166:169], v[108:111]
	v_mfma_f32_16x16x32_bf16 v[140:143], v[156:159], v[170:173], v[140:143]
	v_mfma_f32_16x16x32_bf16 v[36:39], v[156:159], v[188:191], v[36:39]
	v_mfma_f32_16x16x32_bf16 v[44:47], v[160:163], v[166:169], v[44:47]
	v_mfma_f32_16x16x32_bf16 v[48:51], v[160:163], v[170:173], v[48:51]
	v_mfma_f32_16x16x32_bf16 v[52:55], v[160:163], v[176:179], v[52:55]
	v_mfma_f32_16x16x32_bf16 v[40:43], v[160:163], v[188:191], v[40:43]
	v_mfma_f32_16x16x32_bf16 v[144:147], v[156:159], v[176:179], v[144:147]
	s_setprio 0
	ds_read_b128 v[152:155], v12 offset:55360
	ds_read_b128 v[156:159], v12 offset:57664
	ds_read_b128 v[160:163], v12 offset:59968
	ds_read_b128 v[166:169], v12 offset:62272
	ds_read_b128 v[170:173], v139 offset:64
	ds_read_b128 v[176:179], v139 offset:2368
	ds_read_b128 v[184:187], v139 offset:4672
	ds_read_b128 v[188:191], v139 offset:6976
	s_setprio 1
	s_waitcnt lgkmcnt(2)
	v_mfma_f32_16x16x32_bf16 v[84:87], v[152:155], v[176:179], v[84:87]
	s_waitcnt lgkmcnt(0)
	v_mfma_f32_16x16x32_bf16 v[24:27], v[152:155], v[188:191], v[24:27]
	v_mfma_f32_16x16x32_bf16 v[28:31], v[156:159], v[170:173], v[28:31]
	v_mfma_f32_16x16x32_bf16 v[56:59], v[156:159], v[176:179], v[56:59]
	v_mfma_f32_16x16x32_bf16 v[32:35], v[156:159], v[188:191], v[32:35]
	v_mfma_f32_16x16x32_bf16 v[140:143], v[160:163], v[176:179], v[140:143]
	v_mfma_f32_16x16x32_bf16 v[36:39], v[160:163], v[188:191], v[36:39]
	v_mfma_f32_16x16x32_bf16 v[44:47], v[166:169], v[170:173], v[44:47]
	v_mfma_f32_16x16x32_bf16 v[48:51], v[166:169], v[176:179], v[48:51]
	v_mfma_f32_16x16x32_bf16 v[52:55], v[166:169], v[184:187], v[52:55]
	v_mfma_f32_16x16x32_bf16 v[40:43], v[166:169], v[188:191], v[40:43]
	v_mfma_f32_16x16x32_bf16 v[180:183], v[152:155], v[170:173], v[180:183]
	v_mfma_f32_16x16x32_bf16 v[192:195], v[152:155], v[184:187], v[92:95]
	v_mfma_f32_16x16x32_bf16 v[152:155], v[156:159], v[184:187], v[100:103]
	v_mfma_f32_16x16x32_bf16 v[156:159], v[160:163], v[170:173], v[108:111]
	v_mfma_f32_16x16x32_bf16 v[144:147], v[160:163], v[184:187], v[144:147]
	s_setprio 0
	s_waitcnt vmcnt(11)
	v_mov_b32_e32 v16, v224
	v_mov_b32_e32 v17, v225
	v_mov_b32_e32 v18, v226
	v_mov_b32_e32 v19, v227
	ds_write_b128 v14, v[16:19]
	s_waitcnt vmcnt(10)
	v_mov_b32_e32 v20, v228
	v_mov_b32_e32 v21, v229
	v_mov_b32_e32 v22, v230
	v_mov_b32_e32 v23, v231
	ds_write_b128 v14, v[20:23] offset:9216
	s_waitcnt vmcnt(9)
	v_mov_b32_e32 v148, v232
	v_mov_b32_e32 v149, v233
	v_mov_b32_e32 v150, v234
	v_mov_b32_e32 v151, v235
	ds_write_b128 v14, v[148:151] offset:18432
	s_waitcnt vmcnt(8)
	v_mov_b32_e32 v104, v236
	v_mov_b32_e32 v105, v237
	v_mov_b32_e32 v106, v238
	v_mov_b32_e32 v107, v239
	ds_write_b128 v14, v[104:107] offset:27648
	s_waitcnt vmcnt(7)
	v_mov_b32_e32 v96, v244
	v_mov_b32_e32 v97, v245
	v_mov_b32_e32 v98, v246
	v_mov_b32_e32 v99, v247
	ds_write_b128 v14, v[96:99] offset:36864
	s_waitcnt vmcnt(6)
	v_mov_b32_e32 v80, v248
	v_mov_b32_e32 v81, v249
	v_mov_b32_e32 v82, v250
	v_mov_b32_e32 v83, v251
	ds_write_b128 v14, v[80:83] offset:46080
	s_waitcnt lgkmcnt(0)
	s_barrier
	s_nop 0
	s_nop 0
	v_lshlrev_b32_e32 v7, 16, v148
	v_and_b32_e32 v6, 0xffff0000, v148
	v_fmac_f32_e32 v114, v7, v7
	v_lshlrev_b32_e32 v5, 16, v149
	v_fmac_f32_e32 v114, v6, v6
	v_and_b32_e32 v4, 0xffff0000, v149
	v_fmac_f32_e32 v114, v5, v5
	v_and_b32_e32 v175, 0xffff0000, v151
	v_lshlrev_b32_e32 v188, 16, v151
	v_and_b32_e32 v189, 0xffff0000, v150
	v_lshlrev_b32_e32 v190, 16, v150
	v_fmac_f32_e32 v114, v4, v4
	ds_read_b128 v[4:7], v12
	ds_read_b128 v[8:11], v12 offset:2304
	ds_read_b128 v[148:151], v12 offset:4608
	ds_read_b128 v[160:163], v12 offset:6912
	ds_read_b128 v[166:169], v13 offset:18432
	ds_read_b128 v[170:173], v13 offset:20736
	ds_read_b128 v[176:179], v13 offset:23040
	ds_read_b128 v[184:187], v13 offset:25344
	v_fmac_f32_e32 v114, v190, v190
	v_fmac_f32_e32 v114, v189, v189
	v_fmac_f32_e32 v114, v188, v188
	v_fmac_f32_e32 v114, v175, v175
	s_setprio 1
	s_waitcnt lgkmcnt(3)
	v_mfma_f32_16x16x32_bf16 v[180:183], v[4:7], v[166:169], v[180:183]
	s_waitcnt lgkmcnt(2)
	v_mfma_f32_16x16x32_bf16 v[84:87], v[4:7], v[170:173], v[84:87]
	s_waitcnt lgkmcnt(1)
	v_mfma_f32_16x16x32_bf16 v[188:191], v[4:7], v[176:179], v[192:195]
	s_waitcnt lgkmcnt(0)
	v_mfma_f32_16x16x32_bf16 v[4:7], v[4:7], v[184:187], v[24:27]
	v_mfma_f32_16x16x32_bf16 v[24:27], v[8:11], v[166:169], v[28:31]
	v_mfma_f32_16x16x32_bf16 v[28:31], v[8:11], v[170:173], v[56:59]
	v_mfma_f32_16x16x32_bf16 v[56:59], v[8:11], v[176:179], v[152:155]
	v_mfma_f32_16x16x32_bf16 v[8:11], v[8:11], v[184:187], v[32:35]
	v_mfma_f32_16x16x32_bf16 v[32:35], v[148:151], v[166:169], v[156:159]
	v_mfma_f32_16x16x32_bf16 v[140:143], v[148:151], v[170:173], v[140:143]
	v_mfma_f32_16x16x32_bf16 v[36:39], v[148:151], v[184:187], v[36:39]
	v_mfma_f32_16x16x32_bf16 v[44:47], v[160:163], v[166:169], v[44:47]
	v_mfma_f32_16x16x32_bf16 v[48:51], v[160:163], v[170:173], v[48:51]
	v_mfma_f32_16x16x32_bf16 v[52:55], v[160:163], v[176:179], v[52:55]
	v_mfma_f32_16x16x32_bf16 v[40:43], v[160:163], v[184:187], v[40:43]
	v_mfma_f32_16x16x32_bf16 v[144:147], v[148:151], v[176:179], v[144:147]
	s_setprio 0
	ds_read_b128 v[148:151], v12 offset:64
	ds_read_b128 v[152:155], v12 offset:2368
	ds_read_b128 v[156:159], v12 offset:4672
	ds_read_b128 v[160:163], v12 offset:6976
	ds_read_b128 v[166:169], v13 offset:18496
	ds_read_b128 v[170:173], v13 offset:20800
	ds_read_b128 v[176:179], v13 offset:23104
	ds_read_b128 v[184:187], v13 offset:25408
	s_setprio 1
	s_waitcnt lgkmcnt(2)
	v_mfma_f32_16x16x32_bf16 v[84:87], v[148:151], v[170:173], v[84:87]
	s_waitcnt lgkmcnt(0)
	v_mfma_f32_16x16x32_bf16 v[4:7], v[148:151], v[184:187], v[4:7]
	v_mfma_f32_16x16x32_bf16 v[24:27], v[152:155], v[166:169], v[24:27]
	v_mfma_f32_16x16x32_bf16 v[28:31], v[152:155], v[170:173], v[28:31]
	v_mfma_f32_16x16x32_bf16 v[56:59], v[152:155], v[176:179], v[56:59]
	v_mfma_f32_16x16x32_bf16 v[8:11], v[152:155], v[184:187], v[8:11]
	v_mfma_f32_16x16x32_bf16 v[32:35], v[156:159], v[166:169], v[32:35]
	v_mfma_f32_16x16x32_bf16 v[140:143], v[156:159], v[170:173], v[140:143]
	v_mfma_f32_16x16x32_bf16 v[36:39], v[156:159], v[184:187], v[36:39]
	v_mfma_f32_16x16x32_bf16 v[44:47], v[160:163], v[166:169], v[44:47]
	v_mfma_f32_16x16x32_bf16 v[48:51], v[160:163], v[170:173], v[48:51]
	v_mfma_f32_16x16x32_bf16 v[52:55], v[160:163], v[176:179], v[52:55]
	v_mfma_f32_16x16x32_bf16 v[40:43], v[160:163], v[184:187], v[40:43]
	v_mfma_f32_16x16x32_bf16 v[180:183], v[148:151], v[166:169], v[180:183]
	v_mfma_f32_16x16x32_bf16 v[188:191], v[148:151], v[176:179], v[188:191]
	v_mfma_f32_16x16x32_bf16 v[144:147], v[156:159], v[176:179], v[144:147]
	s_setprio 0
	s_waitcnt vmcnt(5)
	v_mov_b32_e32 v16, v200
	v_mov_b32_e32 v17, v201
	v_mov_b32_e32 v18, v202
	v_mov_b32_e32 v19, v203
	ds_write_b128 v14, v[16:19] offset:55296
	s_waitcnt vmcnt(4)
	v_mov_b32_e32 v0, v204
	v_mov_b32_e32 v1, v205
	v_mov_b32_e32 v2, v206
	v_mov_b32_e32 v3, v207
	ds_write_b128 v14, v[0:3] offset:64512
	s_waitcnt vmcnt(3)
	v_mov_b32_e32 v20, v208
	v_mov_b32_e32 v21, v209
	v_mov_b32_e32 v22, v210
	v_mov_b32_e32 v23, v211
	ds_write_b128 v15, v[20:23] offset:64512
	s_waitcnt vmcnt(2)
	v_mov_b32_e32 v108, v212
	v_mov_b32_e32 v109, v213
	v_mov_b32_e32 v110, v214
	v_mov_b32_e32 v111, v215
	ds_write_b128 v119, v[108:111] offset:64512
	s_waitcnt vmcnt(1)
	v_mov_b32_e32 v100, v216
	v_mov_b32_e32 v101, v217
	v_mov_b32_e32 v102, v218
	v_mov_b32_e32 v103, v219
	ds_write_b128 v196, v[100:103] offset:36864
	s_waitcnt vmcnt(0)
	v_mov_b32_e32 v92, v220
	v_mov_b32_e32 v93, v221
	v_mov_b32_e32 v94, v222
	v_mov_b32_e32 v95, v223
	ds_write_b128 v196, v[92:95] offset:46080
	v_lshlrev_b32_e32 v3, 16, v20
	v_and_b32_e32 v2, 0xffff0000, v20
	v_fmac_f32_e32 v114, v3, v3
	v_lshlrev_b32_e32 v1, 16, v21
	v_fmac_f32_e32 v114, v2, v2
	v_and_b32_e32 v0, 0xffff0000, v21
	v_fmac_f32_e32 v114, v1, v1
	s_waitcnt lgkmcnt(0)
	s_barrier
	v_fmac_f32_e32 v114, v0, v0
	ds_read_b128 v[0:3], v12 offset:55296
	ds_read_b128 v[14:17], v12 offset:57600
	ds_read_b128 v[18:21], v12 offset:59904
	ds_read_b128 v[148:151], v12 offset:62208
	ds_read_b128 v[152:155], v139
	ds_read_b128 v[156:159], v139 offset:2304
	ds_read_b128 v[160:163], v139 offset:4608
	ds_read_b128 v[166:169], v139 offset:6912
	v_and_b32_e32 v119, 0xffff0000, v22
	v_lshlrev_b32_e32 v22, 16, v22
	v_fmac_f32_e32 v114, v22, v22
	v_and_b32_e32 v13, 0xffff0000, v23
	v_lshlrev_b32_e32 v23, 16, v23
	v_fmac_f32_e32 v114, v119, v119
	v_fmac_f32_e32 v114, v23, v23
	v_fmac_f32_e32 v114, v13, v13
	s_setprio 1
	s_waitcnt lgkmcnt(3)
	v_mfma_f32_16x16x32_bf16 v[170:173], v[0:3], v[152:155], v[180:183]
	s_waitcnt lgkmcnt(2)
	v_mfma_f32_16x16x32_bf16 v[176:179], v[0:3], v[156:159], v[84:87]
	s_waitcnt lgkmcnt(1)
	v_mfma_f32_16x16x32_bf16 v[180:183], v[0:3], v[160:163], v[188:191]
	s_waitcnt lgkmcnt(0)
	v_mfma_f32_16x16x32_bf16 v[0:3], v[0:3], v[166:169], v[4:7]
	v_mfma_f32_16x16x32_bf16 v[4:7], v[14:17], v[152:155], v[24:27]
	v_mfma_f32_16x16x32_bf16 v[22:25], v[14:17], v[156:159], v[28:31]
	v_mfma_f32_16x16x32_bf16 v[184:187], v[14:17], v[160:163], v[56:59]
	v_mfma_f32_16x16x32_bf16 v[8:11], v[14:17], v[166:169], v[8:11]
	v_mfma_f32_16x16x32_bf16 v[32:35], v[18:21], v[152:155], v[32:35]
	v_mfma_f32_16x16x32_bf16 v[140:143], v[18:21], v[156:159], v[140:143]
	v_mfma_f32_16x16x32_bf16 v[144:147], v[18:21], v[160:163], v[144:147]
	v_mfma_f32_16x16x32_bf16 v[16:19], v[18:21], v[166:169], v[36:39]
	v_mfma_f32_16x16x32_bf16 v[152:155], v[148:151], v[152:155], v[44:47]
	v_mfma_f32_16x16x32_bf16 v[156:159], v[148:151], v[156:159], v[48:51]
	v_mfma_f32_16x16x32_bf16 v[160:163], v[148:151], v[160:163], v[52:55]
	v_mfma_f32_16x16x32_bf16 v[148:151], v[148:151], v[166:169], v[40:43]
	s_setprio 0
	ds_read_b128 v[36:39], v12 offset:55360
	ds_read_b128 v[48:51], v12 offset:57664
	ds_read_b128 v[166:169], v12 offset:59968
	ds_read_b128 v[188:191], v12 offset:62272
	ds_read_b128 v[192:195], v139 offset:64
	ds_read_b128 v[196:199], v139 offset:2368
	ds_read_b128 v[200:203], v139 offset:4672
	ds_read_b128 v[204:207], v139 offset:6976
	s_setprio 1
	s_waitcnt lgkmcnt(3)
	v_mfma_f32_16x16x32_bf16 v[84:87], v[36:39], v[192:195], v[170:173]
	s_waitcnt lgkmcnt(2)
	v_mfma_f32_16x16x32_bf16 v[44:47], v[36:39], v[196:199], v[176:179]
	s_waitcnt lgkmcnt(1)
	v_mfma_f32_16x16x32_bf16 v[28:31], v[36:39], v[200:203], v[180:183]
	s_waitcnt lgkmcnt(0)
	v_mfma_f32_16x16x32_bf16 v[12:15], v[36:39], v[204:207], v[0:3]
	v_mfma_f32_16x16x32_bf16 v[56:59], v[48:51], v[192:195], v[4:7]
	v_mfma_f32_16x16x32_bf16 v[40:43], v[48:51], v[196:199], v[22:25]
	v_mfma_f32_16x16x32_bf16 v[24:27], v[48:51], v[200:203], v[184:187]
	v_mfma_f32_16x16x32_bf16 v[8:11], v[48:51], v[204:207], v[8:11]
	v_mfma_f32_16x16x32_bf16 v[52:55], v[166:169], v[192:195], v[32:35]
	v_mfma_f32_16x16x32_bf16 v[36:39], v[166:169], v[196:199], v[140:143]
	v_mfma_f32_16x16x32_bf16 v[20:23], v[166:169], v[200:203], v[144:147]
	v_mfma_f32_16x16x32_bf16 v[4:7], v[166:169], v[204:207], v[16:19]
	v_mfma_f32_16x16x32_bf16 v[48:51], v[188:191], v[192:195], v[152:155]
	v_mfma_f32_16x16x32_bf16 v[32:35], v[188:191], v[196:199], v[156:159]
	v_mfma_f32_16x16x32_bf16 v[16:19], v[188:191], v[200:203], v[160:163]
	v_mfma_f32_16x16x32_bf16 v[0:3], v[188:191], v[204:207], v[148:151]
	s_setprio 0
	v_cmp_lt_i32_e32 vcc, v129, v130
	s_waitcnt lgkmcnt(0)
	s_barrier
	v_lshl_add_u32 v118, v118, 2, s2
	v_cndmask_b32_e32 v119, v128, v129, vcc
	v_cmp_lt_i32_e32 vcc, v131, v130
	v_lshlrev_b32_e32 v119, 2, v119
	s_nop 0
	v_cndmask_b32_e32 v139, v128, v131, vcc
	v_cmp_lt_i32_e32 vcc, v132, v130
	v_lshlrev_b32_e32 v139, 2, v139
	s_nop 0
	v_cndmask_b32_e32 v140, v128, v132, vcc
	v_cmp_eq_u32_e32 vcc, 0, v138
	ds_bpermute_b32 v138, v119, v114
	v_lshlrev_b32_e32 v140, 2, v140
	s_waitcnt lgkmcnt(0)
	v_add_f32_e32 v114, v114, v138
	ds_bpermute_b32 v138, v139, v114
	s_waitcnt lgkmcnt(0)
	v_add_f32_e32 v114, v114, v138
	ds_bpermute_b32 v138, v140, v114
	s_and_saveexec_b64 s[4:5], vcc
	s_cbranch_execz .LBB0_400
	s_waitcnt lgkmcnt(0)
	v_add_f32_e32 v114, v114, v138
	v_fmamk_f32 v114, v114, 0x3b800000, v133
	v_mul_f32_e32 v138, 0x4b800000, v114
	v_cmp_gt_f32_e64 s[0:1], s68, v114
	s_nop 1
	v_cndmask_b32_e64 v114, v114, v138, s[0:1]
	v_rsq_f32_e32 v114, v114
	s_nop 0
	v_mul_f32_e32 v138, 0x45800000, v114
	v_cndmask_b32_e64 v114, v114, v138, s[0:1]
	ds_write_b32 v118, v114

.LBB0_486:
	v_mov_b32_e32 v0, v174
	s_cmpk_gt_i32 s90, 0x3ff
	s_cbranch_scc1 .LBB0_757
	v_lshrrev_b32_e32 v1, 2, v0
	v_readlane_b32 s36, v240, 1
	s_movk_i32 s0, 0xff
	v_and_b32_e32 v1, 12, v1
	s_movk_i32 s2, 0xc0
	v_readlane_b32 s40, v240, 5
	v_readlane_b32 s41, v240, 6
	v_cmp_lt_u32_e32 vcc, s0, v0
	v_and_or_b32 v166, v0, s2, v1
	v_and_b32_e32 v167, 0xcf, v0
	v_or_b32_e32 v181, 48, v0
	v_lshlrev_b32_e32 v0, 13, v0
	v_readlane_b32 s42, v240, 7
	v_readlane_b32 s43, v240, 8
	v_readlane_b32 s44, v240, 9
	v_readlane_b32 s45, v240, 10
	v_readlane_b32 s46, v240, 11
	v_readlane_b32 s47, v240, 12
	v_readlane_b32 s48, v240, 13
	v_readlane_b32 s49, v240, 14
	v_readlane_b32 s50, v240, 15
	v_readlane_b32 s51, v240, 16
	s_mov_b64 s[4:5], s[40:41]
	v_and_b32_e32 v156, 0x1e000, v0
	v_mov_b32_e32 v157, 0
	s_mov_b64 s[12:13], s[48:49]
	s_add_i32 s3, 0, 0x1b000
	v_or_b32_e32 v169, 16, v166
	v_or_b32_e32 v171, 32, v166
	v_or_b32_e32 v173, 48, v166
	v_or_b32_e32 v177, 16, v167
	v_or_b32_e32 v179, 32, v167
	s_mov_b64 s[8:9], s[44:45]
	s_mov_b64 s[10:11], s[46:47]
	s_mov_b64 s[14:15], s[50:51]
	v_lshl_add_u64 v[158:159], s[12:13], 0, v[156:157]
	v_lshlrev_b32_e32 v156, 1, v1
	v_lshl_add_u32 v168, v166, 2, s3
	v_lshl_add_u32 v170, v169, 2, s3
	v_lshl_add_u32 v172, v171, 2, s3
	v_lshl_add_u32 v175, v173, 2, s3
	v_lshl_add_u32 v176, v167, 2, s3
	v_lshl_add_u32 v178, v177, 2, s3
	v_lshl_add_u32 v180, v179, 2, s3
	v_lshl_add_u32 v182, v181, 2, s3
	v_lshl_add_u64 v[160:161], s[10:11], 0, v[156:157]
	s_lshl_b32 s8, s90, 5
	s_lshl_b32 s9, s88, 5
	s_movk_i32 s10, 0x1040
	s_movk_i32 s11, 0x90
	s_add_i32 s12, 0, 0x12000
	v_mbcnt_hi_u32_b32 v183, -1, v164
	v_mov_b32_e32 v184, 0x358637bd
	s_mov_b32 s13, 0x800000
	v_mov_b32_e32 v185, 0xc0
	s_mov_b32 s14, s90
	v_readlane_b32 s37, v240, 2
	v_readlane_b32 s38, v240, 3
	v_readlane_b32 s39, v240, 4
	s_mov_b64 s[6:7], s[42:43]
	s_mov_b32 s98, s88
	s_movk_i32 s99, 0x400
	s_cmp_lg_u32 s88, 0x100
	s_cbranch_scc1 .Lp3kv_noremap
	s_and_b32 s14, s90, 7
	s_lshl_b32 s14, s14, 7
	s_lshr_b32 s98, s90, 3
	s_add_i32 s14, s14, s98
	s_lshl_b32 s8, s14, 5
	s_add_i32 s99, s14, 0x80
	s_movk_i32 s98, 32
	s_movk_i32 s9, 0x400

.LBB0_488:
	s_or_b64 exec, exec, s[0:1]
	v_cvt_pk_bf16_f32 v2, v2, v3
	s_waitcnt lgkmcnt(0)
	global_store_dword v[0:1], v2, off offset:4
	s_waitcnt lgkmcnt(0)
	s_barrier
	s_add_i32 s14, s14, s98
	s_add_i32 s8, s8, s9
	s_cmp_lt_i32 s14, s99
	s_cbranch_scc0 .LBB0_757
.LBB0_489:
	s_and_b32 s15, s14, 7
	v_readlane_b32 s36, v241, 8
	s_and_b32 s4, s8, 0xffffff00
	s_lshl_b32 s0, s15, 15
	v_readlane_b32 s38, v241, 10
	v_mov_b32_e32 v28, v174
	v_readlane_b32 s39, v241, 11
	s_add_u32 s0, s38, s0
	v_readlane_b32 s37, v241, 9
	v_ashrrev_i32_e32 v162, 3, v28
	v_and_b32_e32 v186, 7, v28
	v_readlane_b32 s40, v241, 12
	v_readlane_b32 s41, v241, 13
	v_readlane_b32 s42, v241, 14
	v_readlane_b32 s43, v241, 15
	s_addc_u32 s1, s39, 0
	v_lshlrev_b32_e32 v156, 4, v186
	v_ashrrev_i32_e32 v163, 31, v162
	v_readlane_b32 s36, v240, 1
	v_lshl_add_u64 v[0:1], s[0:1], 0, v[156:157]
	v_lshlrev_b64 v[2:3], 8, v[162:163]
	s_mul_hi_i32 s5, s4, 0x1040
	s_mulk_i32 s4, 0x1040
	v_readlane_b32 s40, v240, 5
	v_lshl_add_u64 v[20:21], v[0:1], 0, v[2:3]
	v_add_u32_e32 v2, 64, v162
	v_readlane_b32 s41, v240, 6
	s_add_u32 s4, s40, s4
	v_ashrrev_i32_e32 v3, 31, v2
	s_addc_u32 s5, s41, s5
	v_lshlrev_b64 v[4:5], 8, v[2:3]
	global_load_dwordx4 v[8:11], v[20:21], off
	v_lshl_add_u64 v[22:23], v[0:1], 0, v[4:5]
	v_lshl_add_u64 v[0:1], s[4:5], 0, v[156:157]
	global_load_dwordx4 v[16:19], v[22:23], off
	v_mad_i64_i32 v[32:33], s[0:1], v162, s10, v[0:1]
	global_load_dwordx4 v[24:27], v[32:33], off offset:512
	v_mad_i64_i32 v[40:41], s[0:1], v2, s10, v[0:1]
	v_add_u32_e32 v2, 0x80, v162
	global_load_dwordx4 v[12:15], v[40:41], off offset:512
	v_mad_i64_i32 v[42:43], s[0:1], v2, s10, v[0:1]
	v_add_u32_e32 v2, 0xc0, v162
	global_load_dwordx4 v[4:7], v[42:43], off offset:512
	v_mad_i64_i32 v[44:45], s[0:1], v2, s10, v[0:1]
	global_load_dwordx4 v[0:3], v[44:45], off offset:512
	global_load_dwordx4 v[200:203], v[20:21], off offset:128
	global_load_dwordx4 v[204:207], v[22:23], off offset:128
	global_load_dwordx4 v[208:211], v[32:33], off offset:640
	global_load_dwordx4 v[212:215], v[40:41], off offset:640
	global_load_dwordx4 v[216:219], v[42:43], off offset:640
	global_load_dwordx4 v[220:223], v[44:45], off offset:640
	v_add_u32_e32 v31, 0, v156
	v_mul_lo_u32 v34, v162, s11
	v_add_u32_e32 v140, v31, v34
	v_ashrrev_i32_e32 v29, 8, v28
	v_and_b32_e32 v30, 15, v28
	v_and_b32_e32 v142, 48, v28
	v_and_b32_e32 v112, 0xcf, v28
	v_cmp_ne_u32_e64 s[0:1], 1, v29
	v_add_u32_e32 v113, 0, v142
	v_readlane_b32 s37, v240, 2
	v_readlane_b32 s38, v240, 3
	v_readlane_b32 s39, v240, 4
	v_readlane_b32 s42, v240, 7
	v_readlane_b32 s43, v240, 8
	v_readlane_b32 s44, v240, 9
	v_readlane_b32 s45, v240, 10
	v_readlane_b32 s46, v240, 11
	v_readlane_b32 s47, v240, 12
	v_readlane_b32 s48, v240, 13
	v_readlane_b32 s49, v240, 14
	v_readlane_b32 s50, v240, 15
	v_readlane_b32 s51, v240, 16
	s_waitcnt vmcnt(11)
	ds_write_b128 v140, v[8:11]
	s_waitcnt vmcnt(10)
	ds_write_b128 v140, v[16:19] offset:9216
	v_add_u32_e32 v8, 0x4800, v34
	v_add_u32_e32 v141, v31, v8
	s_waitcnt vmcnt(9)
	ds_write_b128 v141, v[24:27]
	s_waitcnt vmcnt(8)
	ds_write_b128 v141, v[12:15] offset:9216
	s_waitcnt vmcnt(7)
	ds_write_b128 v140, v[4:7] offset:36864
	s_waitcnt vmcnt(6)
	ds_write_b128 v140, v[0:3] offset:46080
	s_waitcnt lgkmcnt(0)
	s_barrier
	v_lshl_or_b32 v8, v29, 6, v30
	v_mul_lo_u32 v46, v8, s11
	s_nop 0
	s_nop 0
	v_add_u32_e32 v156, v113, v46
	v_mad_u32_u24 v44, v112, s11, v113
	ds_read_b128 v[48:51], v156
	ds_read_b128 v[52:55], v156 offset:2304
	ds_read_b128 v[60:63], v156 offset:4608
	ds_read_b128 v[68:71], v156 offset:6912
	ds_read_b128 v[64:67], v44 offset:18432
	ds_read_b128 v[40:43], v44 offset:20736
	ds_read_b128 v[104:107], v44 offset:23040
	ds_read_b128 v[108:111], v44 offset:25344
	s_setprio 1
	s_and_saveexec_b64 s[4:5], s[0:1]
	s_xor_b64 s[4:5], exec, s[4:5]
	s_cbranch_execz .LBB0_491
	s_waitcnt lgkmcnt(3)
	v_mfma_f32_16x16x32_bf16 v[72:75], v[48:51], v[64:67], 0
	s_andn2_saveexec_b64 s[4:5], s[4:5]
	s_cbranch_execz .LBB0_493
	s_branch .LBB0_492

.LBB0_617:
	s_or_b64 exec, exec, s[4:5]
	s_setprio 0
	s_waitcnt vmcnt(5)
	v_mov_b32_e32 v28, v200
	v_mov_b32_e32 v29, v201
	v_mov_b32_e32 v30, v202
	v_mov_b32_e32 v31, v203
	ds_write_b128 v140, v[28:31] offset:55296
	s_waitcnt vmcnt(4)
	v_mov_b32_e32 v36, v204
	v_mov_b32_e32 v37, v205
	v_mov_b32_e32 v38, v206
	v_mov_b32_e32 v39, v207
	ds_write_b128 v140, v[36:39] offset:64512
	s_waitcnt vmcnt(3)
	v_mov_b32_e32 v32, v208
	v_mov_b32_e32 v33, v209
	v_mov_b32_e32 v34, v210
	v_mov_b32_e32 v35, v211
	ds_write_b128 v141, v[32:35] offset:55296
	s_waitcnt vmcnt(2)
	v_mov_b32_e32 v20, v212
	v_mov_b32_e32 v21, v213
	v_mov_b32_e32 v22, v214
	v_mov_b32_e32 v23, v215
	ds_write_b128 v141, v[20:23] offset:64512
	v_add_u32_e32 v28, 0x16800, v140
	s_waitcnt vmcnt(1)
	v_mov_b32_e32 v16, v216
	v_mov_b32_e32 v17, v217
	v_mov_b32_e32 v18, v218
	v_mov_b32_e32 v19, v219
	ds_write_b128 v28, v[16:19]
	v_add_u32_e32 v28, 0x18c00, v140
	s_waitcnt vmcnt(0)
	v_mov_b32_e32 v8, v220
	v_mov_b32_e32 v9, v221
	v_mov_b32_e32 v10, v222
	v_mov_b32_e32 v11, v223
	ds_write_b128 v28, v[8:11]
	v_add_u32_e32 v28, s12, v142
	s_waitcnt lgkmcnt(0)
	s_barrier
	v_add_u32_e32 v163, v28, v143
	s_waitcnt lgkmcnt(6)
	ds_read_b128 v[112:115], v156 offset:55296
	ds_read_b128 v[124:127], v156 offset:57600
	ds_read_b128 v[148:151], v156 offset:59904
	ds_read_b128 v[132:135], v156 offset:62208
	ds_read_b128 v[144:147], v163
	ds_read_b128 v[104:107], v163 offset:2304
	ds_read_b128 v[140:143], v163 offset:4608
	ds_read_b128 v[136:139], v163 offset:6912
	s_setprio 1
	s_and_saveexec_b64 s[4:5], s[0:1]
	s_xor_b64 s[4:5], exec, s[4:5]
	s_cbranch_execz .LBB0_619
	s_waitcnt lgkmcnt(3)
	v_mfma_f32_16x16x32_bf16 v[28:31], v[112:115], v[144:147], v[68:71]
	s_andn2_saveexec_b64 s[4:5], s[4:5]
	s_cbranch_execz .LBB0_621
	s_branch .LBB0_620
